# third measurement of the final candidate (unchanged file)
# baseline (speedup 1.0000x reference)
.LBB0_67:
	s_and_b32 s0, s25, 0xffffffc0
	v_writelane_b32 v253, s0, 5
	v_mbcnt_lo_u32_b32 v1, -1, 0
	v_readlane_b32 s0, v253, 0
	v_readlane_b32 s4, v253, 2
	v_readlane_b32 s1, v253, 1
	v_readlane_b32 s5, v253, 3
	s_mul_i32 s0, s1, s0
	s_load_dword s1, s[4:5], 0x378
	s_mov_b32 s92, 1
	v_mov_b32_e32 v0, 0
	s_movk_i32 s93, 0x1ff
	v_mov_b32_e32 v223, 0x358637bd
	s_waitcnt lgkmcnt(0)
	s_mul_i32 s0, s0, s1
	v_writelane_b32 v253, s0, 6
	s_mov_b32 s0, 0
	v_writelane_b32 v255, s0, 63
	s_add_u32 s0, s2, 0x1d800200
	s_addc_u32 s1, s3, 0
	v_writelane_b32 v253, s0, 7
	v_mbcnt_hi_u32_b32 v224, -1, v1
	v_mov_b32_e32 v225, 0x4000
	v_writelane_b32 v253, s1, 8
	s_add_u32 s0, s2, 0x1d800400
	s_addc_u32 s1, s3, 0
	v_writelane_b32 v253, s0, 9
	v_mov_b32_e32 v226, 0x8000
	v_mov_b32_e32 v227, 0x2000
	v_writelane_b32 v253, s1, 10
	s_add_u32 s0, s2, 0x1d800500
	s_addc_u32 s1, s3, 0
	v_writelane_b32 v253, s0, 11
	v_mov_b32_e32 v228, 0x1000
	v_mov_b32_e32 v229, 0x800
	v_writelane_b32 v253, s1, 12
	s_add_u32 s0, s2, 0x1d800600
	s_addc_u32 s1, s3, 0
	v_writelane_b32 v253, s0, 13
	v_mov_b32_e32 v230, 0x400
	v_mov_b64_e32 v[162:163], 0x200
	v_writelane_b32 v253, s1, 14
	s_add_u32 s0, s2, 0x1d800700
	s_addc_u32 s1, s3, 0
	v_writelane_b32 v253, s0, 15
	v_mov_b64_e32 v[164:165], 0x1ff
	v_mov_b64_e32 v[166:167], 0xaff
	v_writelane_b32 v253, s1, 16
	s_add_u32 s0, s2, 0x1d800800
	s_addc_u32 s1, s3, 0
	v_writelane_b32 v253, s0, 17
	v_mov_b32_e32 v231, 0x80
	v_mov_b32_e32 v232, 0x100
	v_writelane_b32 v253, s1, 18
	s_add_u32 s0, s2, 0x1d800900
	s_addc_u32 s1, s3, 0
	v_writelane_b32 v253, s0, 19
	v_mov_b32_e32 v233, 0x200
	v_mov_b32_e32 v234, 0xf149f2ca
	v_writelane_b32 v253, s1, 20
	s_add_u32 s0, s2, 0x1d800a00
	s_addc_u32 s1, s3, 0
	v_writelane_b32 v253, s0, 21
	s_mov_b32 s95, 0x800000
	s_movk_i32 s96, 0x200
	v_writelane_b32 v253, s1, 22
	s_add_u32 s0, s2, 0x1d800b00
	s_addc_u32 s1, s3, 0
	v_writelane_b32 v253, s0, 23
	s_mov_b32 s97, 0x38e38e39
	s_mov_b32 s33, 0x3e38aa3b
	v_writelane_b32 v253, s1, 24
	s_add_u32 s0, s2, 0x1d800c00
	s_addc_u32 s1, s3, 0
	v_writelane_b32 v253, s0, 25
	s_movk_i32 s61, 0x17f
	s_movk_i32 s62, 0x300
	v_writelane_b32 v253, s1, 26
	s_add_u32 s0, s2, 0x1d800d00
	s_addc_u32 s1, s3, 0
	v_writelane_b32 v253, s0, 27
	s_movk_i32 s63, 0x180
	s_movk_i32 s82, 0x1800
	v_writelane_b32 v253, s1, 28
	s_add_u32 s0, s2, 0x1d800e00
	s_addc_u32 s1, s3, 0
	v_writelane_b32 v253, s0, 29
	s_mov_b64 s[84:85], 0x80
	s_mov_b32 s89, 0
	v_writelane_b32 v253, s1, 30
	s_add_u32 s0, s2, 0x1d800f00
	s_addc_u32 s1, s3, 0
	v_writelane_b32 v253, s0, 31
	s_nop 1
	v_writelane_b32 v253, s1, 32
	s_add_u32 s0, s2, 0x1d801000
	s_addc_u32 s1, s3, 0
	v_writelane_b32 v253, s0, 33
	s_nop 1
	v_writelane_b32 v253, s1, 34
	s_add_u32 s0, s2, 0x1d801100
	s_addc_u32 s1, s3, 0
	v_writelane_b32 v253, s0, 35
	s_nop 1
	v_writelane_b32 v253, s1, 36
	s_add_u32 s0, s2, 0x1d801200
	s_addc_u32 s1, s3, 0
	v_writelane_b32 v253, s0, 37
	s_nop 1
	v_writelane_b32 v253, s1, 38
	s_add_u32 s0, s2, 0x1d801300
	s_addc_u32 s1, s3, 0
	v_writelane_b32 v253, s0, 39
	s_cmp_eq_u32 s24, 15
	s_nop 0
	v_writelane_b32 v253, s1, 40
	s_cselect_b64 s[0:1], -1, 0
	v_writelane_b32 v253, s0, 41
	s_cmp_eq_u32 s24, 14
	s_nop 0
	v_writelane_b32 v253, s1, 42
	s_cselect_b64 s[0:1], -1, 0
	v_writelane_b32 v253, s0, 43
	s_cmp_eq_u32 s24, 13
	s_nop 0
	v_writelane_b32 v253, s1, 44
	s_cselect_b64 s[0:1], -1, 0
	v_writelane_b32 v253, s0, 45
	s_cmp_eq_u32 s24, 12
	s_nop 0
	v_writelane_b32 v253, s1, 46
	s_cselect_b64 s[0:1], -1, 0
	v_writelane_b32 v253, s0, 47
	s_cmp_eq_u32 s24, 11
	s_nop 0
	v_writelane_b32 v253, s1, 48
	s_cselect_b64 s[0:1], -1, 0
	v_writelane_b32 v253, s0, 49
	s_cmp_eq_u32 s24, 10
	s_nop 0
	v_writelane_b32 v253, s1, 50
	s_cselect_b64 s[0:1], -1, 0
	v_writelane_b32 v253, s0, 51
	s_cmp_eq_u32 s24, 9
	s_nop 0
	v_writelane_b32 v253, s1, 52
	s_cselect_b64 s[0:1], -1, 0
	v_writelane_b32 v253, s0, 53
	s_cmp_eq_u32 s24, 8
	s_nop 0
	v_writelane_b32 v253, s1, 54
	s_cselect_b64 s[0:1], -1, 0
	v_writelane_b32 v253, s0, 55
	s_cmp_eq_u32 s24, 7
	s_nop 0
	v_writelane_b32 v253, s1, 56
	s_cselect_b64 s[0:1], -1, 0
	v_writelane_b32 v253, s0, 57
	s_cmp_eq_u32 s24, 6
	s_nop 0
	v_writelane_b32 v253, s1, 58
	s_cselect_b64 s[0:1], -1, 0
	v_writelane_b32 v253, s0, 59
	s_cmp_eq_u32 s24, 5
	s_nop 0
	v_writelane_b32 v253, s1, 60
	s_cselect_b64 s[0:1], -1, 0
	v_writelane_b32 v253, s0, 61
	s_cmp_eq_u32 s24, 4
	s_nop 0
	v_writelane_b32 v253, s1, 62
	s_cselect_b64 s[0:1], -1, 0
	v_writelane_b32 v253, s0, 63
	s_cmp_eq_u32 s24, 3
	s_nop 0
	v_writelane_b32 v254, s1, 0
	s_cselect_b64 s[0:1], -1, 0
	v_writelane_b32 v254, s0, 1
	s_cmp_eq_u32 s24, 2
	s_nop 0
	v_writelane_b32 v254, s1, 2
	s_cselect_b64 s[0:1], -1, 0
	v_writelane_b32 v254, s0, 3
	s_cmp_eq_u32 s24, 1
	s_nop 0
	v_writelane_b32 v254, s1, 4
	s_cselect_b64 s[0:1], -1, 0
	v_writelane_b32 v254, s0, 5
	s_cmp_eq_u32 s24, 0
	s_nop 0
	v_writelane_b32 v254, s1, 6
	s_cselect_b64 s[0:1], -1, 0
	v_writelane_b32 v254, s0, 7
	s_nop 1
	v_writelane_b32 v254, s1, 8
	s_lshl_b32 s0, s24, 8
	s_add_u32 s0, s12, s0
	s_addc_u32 s1, s13, 0
	s_add_u32 s4, s0, 0x1400
	s_addc_u32 s5, s1, 0
	v_writelane_b32 v254, s4, 9
	s_add_u32 s0, s0, 0x2400
	s_addc_u32 s1, s1, 0
	v_writelane_b32 v254, s5, 10
	v_writelane_b32 v254, s0, 11
	s_nop 1
	v_writelane_b32 v254, s1, 12
	s_add_u32 s0, s2, 0x1d803400
	s_addc_u32 s1, s3, 0
	v_writelane_b32 v254, s0, 13
	s_nop 1
	v_writelane_b32 v254, s1, 14
	s_add_u32 s0, s2, 0x1d803500
	s_addc_u32 s1, s3, 0
	v_writelane_b32 v254, s0, 15
	s_nop 1
	v_writelane_b32 v254, s1, 16
	s_add_i32 s0, 0, 0x24000
	v_writelane_b32 v254, s0, 17
	s_add_i32 s0, 0, 0x24004
	v_writelane_b32 v254, s0, 18
	s_add_i32 s0, 0, 0x1b000
	v_writelane_b32 v254, s0, 19
	v_writelane_b32 v254, s80, 20
	s_branch .LBB0_70

.LBB0_69:
	s_cmp_lg_u32 s92, 17
	s_cbranch_scc1 .Lprobe_norepeat
	v_readlane_b32 s0, v255, 63
	s_nop 0
	s_cmp_ge_u32 s0, 2
	s_cbranch_scc1 .Lprobe_norepeat
	s_add_i32 s0, s0, 1
	v_writelane_b32 v255, s0, 63
	s_mov_b32 s92, 16

.LBB0_345:
	s_waitcnt vmcnt(0)
	s_add_i32 s69, s8, 1
	s_cmp_ge_i32 s69, s71
	s_waitcnt lgkmcnt(0)
	s_barrier
	s_cbranch_scc1 .LBB0_352
	v_readlane_b32 s0, v255, 63
	s_nop 0
	s_cmp_eq_u32 s0, 1
	s_cbranch_scc1 .LBB0_352
	s_bitcmp1_b32 s69, 0
	s_cselect_b32 s0, 0x9000, 0
	s_andn2_b64 vcc, exec, s[74:75]
	s_add_i32 s0, s0, 0
	s_cbranch_vccz .LBB0_372
	s_andn2_b64 vcc, exec, s[76:77]
	s_cbranch_vccz .LBB0_373
